# sg_sample causal mixing loop: 8 weights + 8 LDS rows fetched up front, one wait, same FMA order (was one dependent global load per j)
# speedup vs baseline: 1.0192x; 1.0006x over previous
; #define LAS __attribute__((address_space(3)))
; __device__ __forceinline__ u32x2 pack4(f32x4 v) { u32x2 r; r[0] = cvt_pk(v[0], v[1]); r[1] = cvt_pk(v[2], v[3]); return r; }
; __device__ __forceinline__ f32x4 unpack4(u32x2 u) { f32x4 r; r[0] = bflo(u[0]); r[1] = bfhi(u[0]); r[2] = bflo(u[1]); r[3] = bfhi(u[1]); return r; }
; __device__ __forceinline__ void mix_sg_sample(const Params& p, LAS unsigned char* lds, int b) {
;     ...
;   for (int g = 0; g < 4; ++g) {
;     const int col = g * 256 + 4 * lane;
;     const float bias = p.in[10][g * 128 + w];
;     f32x4 z = (f32x4){bias, bias, bias, bias};
;     for (int j = 0; j <= w; ++j) {
;       const float wv = p.in[9][((size_t)g * 128 + w) * 128 + j];
;       z += *(const LAS f32x4*)(vs + j * 1024 + col) * wv;
;     }
;     const f32x4 uu = unpack4(*(const u32x2*)(U + (size_t)(r0 + w) * 1024 + col));
;     *(u32x2*)(ACAT + (size_t)(r0 + w) * 4096 + col) = pack4(uu * z);
;   }
.LBB0_199:
	v_readfirstlane_b32 s36, v5
	global_load_dwordx4 v[100:103], v[2:3], off
	global_load_dwordx4 v[104:107], v[2:3], off offset:16
	ds_read_b128 v[108:111], v4
	ds_read_b128 v[112:115], v4 offset:4096
	ds_read_b128 v[116:119], v4 offset:8192
	ds_read_b128 v[120:123], v4 offset:12288
	ds_read_b128 v[124:127], v4 offset:16384
	ds_read_b128 v[128:131], v4 offset:20480
	ds_read_b128 v[132:135], v4 offset:24576
	ds_read_b128 v[136:139], v4 offset:28672
	s_waitcnt vmcnt(0) lgkmcnt(0)
	v_mov_b32_e32 v140, v100
	v_pk_fma_f32 v[14:15], v[110:111], v[140:141], v[14:15] op_sel_hi:[1,0,1]
	v_pk_fma_f32 v[0:1], v[108:109], v[140:141], v[0:1] op_sel_hi:[1,0,1]
	s_cmp_lt_u32 s36, 2
	s_cbranch_scc1 .Lsg_done_199
	v_mov_b32_e32 v140, v101
	v_pk_fma_f32 v[14:15], v[114:115], v[140:141], v[14:15] op_sel_hi:[1,0,1]
	v_pk_fma_f32 v[0:1], v[112:113], v[140:141], v[0:1] op_sel_hi:[1,0,1]
	s_cmp_lt_u32 s36, 3
	s_cbranch_scc1 .Lsg_done_199
	v_mov_b32_e32 v140, v102
	v_pk_fma_f32 v[14:15], v[118:119], v[140:141], v[14:15] op_sel_hi:[1,0,1]
	v_pk_fma_f32 v[0:1], v[116:117], v[140:141], v[0:1] op_sel_hi:[1,0,1]
	s_cmp_lt_u32 s36, 4
	s_cbranch_scc1 .Lsg_done_199
	v_mov_b32_e32 v140, v103
	v_pk_fma_f32 v[14:15], v[122:123], v[140:141], v[14:15] op_sel_hi:[1,0,1]
	v_pk_fma_f32 v[0:1], v[120:121], v[140:141], v[0:1] op_sel_hi:[1,0,1]
	s_cmp_lt_u32 s36, 5
	s_cbranch_scc1 .Lsg_done_199
	v_mov_b32_e32 v140, v104
	v_pk_fma_f32 v[14:15], v[126:127], v[140:141], v[14:15] op_sel_hi:[1,0,1]
	v_pk_fma_f32 v[0:1], v[124:125], v[140:141], v[0:1] op_sel_hi:[1,0,1]
	s_cmp_lt_u32 s36, 6
	s_cbranch_scc1 .Lsg_done_199
	v_mov_b32_e32 v140, v105
	v_pk_fma_f32 v[14:15], v[130:131], v[140:141], v[14:15] op_sel_hi:[1,0,1]
	v_pk_fma_f32 v[0:1], v[128:129], v[140:141], v[0:1] op_sel_hi:[1,0,1]
	s_cmp_lt_u32 s36, 7
	s_cbranch_scc1 .Lsg_done_199
	v_mov_b32_e32 v140, v106
	v_pk_fma_f32 v[14:15], v[134:135], v[140:141], v[14:15] op_sel_hi:[1,0,1]
	v_pk_fma_f32 v[0:1], v[132:133], v[140:141], v[0:1] op_sel_hi:[1,0,1]
	s_cmp_lt_u32 s36, 8
	s_cbranch_scc1 .Lsg_done_199
	v_mov_b32_e32 v140, v107
	v_pk_fma_f32 v[14:15], v[138:139], v[140:141], v[14:15] op_sel_hi:[1,0,1]
	v_pk_fma_f32 v[0:1], v[136:137], v[140:141], v[0:1] op_sel_hi:[1,0,1]
.Lsg_done_199:
	s_lshl_b32 s37, s36, 12
	v_add_u32_e32 v4, s37, v4
	s_lshl_b32 s37, s36, 2
	v_mov_b32_e32 v140, s37
	v_mov_b32_e32 v141, 0
	v_lshl_add_u64 v[2:3], v[2:3], 0, v[140:141]
	v_mov_b32_e32 v5, 0
	s_mov_b64 s[40:41], exec
	s_or_b64 exec, exec, s[40:41]
	v_mov_b64_e32 v[4:5], v[2:3]
	v_mov_b64_e32 v[2:3], v[0:1]
	v_mov_b32_e32 v0, v15

; #define LAS __attribute__((address_space(3)))
; __device__ __forceinline__ u32x2 pack4(f32x4 v) { u32x2 r; r[0] = cvt_pk(v[0], v[1]); r[1] = cvt_pk(v[2], v[3]); return r; }
; __device__ __forceinline__ f32x4 unpack4(u32x2 u) { f32x4 r; r[0] = bflo(u[0]); r[1] = bfhi(u[0]); r[2] = bflo(u[1]); r[3] = bfhi(u[1]); return r; }
; __device__ __forceinline__ void mix_sg_sample(const Params& p, LAS unsigned char* lds, int b) {
;     ...
;   for (int g = 0; g < 4; ++g) {
;     const int col = g * 256 + 4 * lane;
;     const float bias = p.in[10][g * 128 + w];
;     f32x4 z = (f32x4){bias, bias, bias, bias};
;     for (int j = 0; j <= w; ++j) {
;       const float wv = p.in[9][((size_t)g * 128 + w) * 128 + j];
;       z += *(const LAS f32x4*)(vs + j * 1024 + col) * wv;
;     }
;     const f32x4 uu = unpack4(*(const u32x2*)(U + (size_t)(r0 + w) * 1024 + col));
;     *(u32x2*)(ACAT + (size_t)(r0 + w) * 4096 + col) = pack4(uu * z);
;   }
.LBB0_203:
	v_readfirstlane_b32 s36, v4
	global_load_dwordx4 v[100:103], v[2:3], off
	global_load_dwordx4 v[104:107], v[2:3], off offset:16
	ds_read_b128 v[108:111], v5
	ds_read_b128 v[112:115], v5 offset:4096
	ds_read_b128 v[116:119], v5 offset:8192
	ds_read_b128 v[120:123], v5 offset:12288
	ds_read_b128 v[124:127], v5 offset:16384
	ds_read_b128 v[128:131], v5 offset:20480
	ds_read_b128 v[132:135], v5 offset:24576
	ds_read_b128 v[136:139], v5 offset:28672
	s_waitcnt vmcnt(0) lgkmcnt(0)
	v_mov_b32_e32 v140, v100
	v_pk_fma_f32 v[14:15], v[110:111], v[140:141], v[14:15] op_sel_hi:[1,0,1]
	v_pk_fma_f32 v[0:1], v[108:109], v[140:141], v[0:1] op_sel_hi:[1,0,1]
	s_cmp_lt_u32 s36, 2
	s_cbranch_scc1 .Lsg_done_203
	v_mov_b32_e32 v140, v101
	v_pk_fma_f32 v[14:15], v[114:115], v[140:141], v[14:15] op_sel_hi:[1,0,1]
	v_pk_fma_f32 v[0:1], v[112:113], v[140:141], v[0:1] op_sel_hi:[1,0,1]
	s_cmp_lt_u32 s36, 3
	s_cbranch_scc1 .Lsg_done_203
	v_mov_b32_e32 v140, v102
	v_pk_fma_f32 v[14:15], v[118:119], v[140:141], v[14:15] op_sel_hi:[1,0,1]
	v_pk_fma_f32 v[0:1], v[116:117], v[140:141], v[0:1] op_sel_hi:[1,0,1]
	s_cmp_lt_u32 s36, 4
	s_cbranch_scc1 .Lsg_done_203
	v_mov_b32_e32 v140, v103
	v_pk_fma_f32 v[14:15], v[122:123], v[140:141], v[14:15] op_sel_hi:[1,0,1]
	v_pk_fma_f32 v[0:1], v[120:121], v[140:141], v[0:1] op_sel_hi:[1,0,1]
	s_cmp_lt_u32 s36, 5
	s_cbranch_scc1 .Lsg_done_203
	v_mov_b32_e32 v140, v104
	v_pk_fma_f32 v[14:15], v[126:127], v[140:141], v[14:15] op_sel_hi:[1,0,1]
	v_pk_fma_f32 v[0:1], v[124:125], v[140:141], v[0:1] op_sel_hi:[1,0,1]
	s_cmp_lt_u32 s36, 6
	s_cbranch_scc1 .Lsg_done_203
	v_mov_b32_e32 v140, v105
	v_pk_fma_f32 v[14:15], v[130:131], v[140:141], v[14:15] op_sel_hi:[1,0,1]
	v_pk_fma_f32 v[0:1], v[128:129], v[140:141], v[0:1] op_sel_hi:[1,0,1]
	s_cmp_lt_u32 s36, 7
	s_cbranch_scc1 .Lsg_done_203
	v_mov_b32_e32 v140, v106
	v_pk_fma_f32 v[14:15], v[134:135], v[140:141], v[14:15] op_sel_hi:[1,0,1]
	v_pk_fma_f32 v[0:1], v[132:133], v[140:141], v[0:1] op_sel_hi:[1,0,1]
	s_cmp_lt_u32 s36, 8
	s_cbranch_scc1 .Lsg_done_203
	v_mov_b32_e32 v140, v107
	v_pk_fma_f32 v[14:15], v[138:139], v[140:141], v[14:15] op_sel_hi:[1,0,1]
	v_pk_fma_f32 v[0:1], v[136:137], v[140:141], v[0:1] op_sel_hi:[1,0,1]
.Lsg_done_203:
	s_lshl_b32 s37, s36, 12
	v_add_u32_e32 v5, s37, v5
	s_lshl_b32 s37, s36, 2
	v_mov_b32_e32 v140, s37
	v_mov_b32_e32 v141, 0
	v_lshl_add_u64 v[2:3], v[2:3], 0, v[140:141]
	v_mov_b32_e32 v4, 0
	s_mov_b64 s[40:41], exec
	s_or_b64 exec, exec, s[40:41]
	v_mov_b64_e32 v[4:5], v[2:3]
	v_mov_b64_e32 v[2:3], v[0:1]
	v_mov_b32_e32 v0, v15

; #define LAS __attribute__((address_space(3)))
; __device__ __forceinline__ u32x2 pack4(f32x4 v) { u32x2 r; r[0] = cvt_pk(v[0], v[1]); r[1] = cvt_pk(v[2], v[3]); return r; }
; __device__ __forceinline__ f32x4 unpack4(u32x2 u) { f32x4 r; r[0] = bflo(u[0]); r[1] = bfhi(u[0]); r[2] = bflo(u[1]); r[3] = bfhi(u[1]); return r; }
; __device__ __forceinline__ void mix_sg_sample(const Params& p, LAS unsigned char* lds, int b) {
;     ...
;   for (int g = 0; g < 4; ++g) {
;     const int col = g * 256 + 4 * lane;
;     const float bias = p.in[10][g * 128 + w];
;     f32x4 z = (f32x4){bias, bias, bias, bias};
;     for (int j = 0; j <= w; ++j) {
;       const float wv = p.in[9][((size_t)g * 128 + w) * 128 + j];
;       z += *(const LAS f32x4*)(vs + j * 1024 + col) * wv;
;     }
;     const f32x4 uu = unpack4(*(const u32x2*)(U + (size_t)(r0 + w) * 1024 + col));
;     *(u32x2*)(ACAT + (size_t)(r0 + w) * 4096 + col) = pack4(uu * z);
;   }
.LBB0_211:
	v_readfirstlane_b32 s40, v16
	global_load_dwordx4 v[100:103], v[2:3], off
	global_load_dwordx4 v[104:107], v[2:3], off offset:16
	ds_read_b128 v[108:111], v4
	ds_read_b128 v[112:115], v4 offset:4096
	ds_read_b128 v[116:119], v4 offset:8192
	ds_read_b128 v[120:123], v4 offset:12288
	ds_read_b128 v[124:127], v4 offset:16384
	ds_read_b128 v[128:131], v4 offset:20480
	ds_read_b128 v[132:135], v4 offset:24576
	ds_read_b128 v[136:139], v4 offset:28672
	s_waitcnt vmcnt(0) lgkmcnt(0)
	v_mov_b32_e32 v140, v100
	v_pk_fma_f32 v[12:13], v[110:111], v[140:141], v[12:13] op_sel_hi:[1,0,1]
	v_pk_fma_f32 v[0:1], v[108:109], v[140:141], v[0:1] op_sel_hi:[1,0,1]
	s_cmp_lt_u32 s40, 2
	s_cbranch_scc1 .Lsg_done_211
	v_mov_b32_e32 v140, v101
	v_pk_fma_f32 v[12:13], v[114:115], v[140:141], v[12:13] op_sel_hi:[1,0,1]
	v_pk_fma_f32 v[0:1], v[112:113], v[140:141], v[0:1] op_sel_hi:[1,0,1]
	s_cmp_lt_u32 s40, 3
	s_cbranch_scc1 .Lsg_done_211
	v_mov_b32_e32 v140, v102
	v_pk_fma_f32 v[12:13], v[118:119], v[140:141], v[12:13] op_sel_hi:[1,0,1]
	v_pk_fma_f32 v[0:1], v[116:117], v[140:141], v[0:1] op_sel_hi:[1,0,1]
	s_cmp_lt_u32 s40, 4
	s_cbranch_scc1 .Lsg_done_211
	v_mov_b32_e32 v140, v103
	v_pk_fma_f32 v[12:13], v[122:123], v[140:141], v[12:13] op_sel_hi:[1,0,1]
	v_pk_fma_f32 v[0:1], v[120:121], v[140:141], v[0:1] op_sel_hi:[1,0,1]
	s_cmp_lt_u32 s40, 5
	s_cbranch_scc1 .Lsg_done_211
	v_mov_b32_e32 v140, v104
	v_pk_fma_f32 v[12:13], v[126:127], v[140:141], v[12:13] op_sel_hi:[1,0,1]
	v_pk_fma_f32 v[0:1], v[124:125], v[140:141], v[0:1] op_sel_hi:[1,0,1]
	s_cmp_lt_u32 s40, 6
	s_cbranch_scc1 .Lsg_done_211
	v_mov_b32_e32 v140, v105
	v_pk_fma_f32 v[12:13], v[130:131], v[140:141], v[12:13] op_sel_hi:[1,0,1]
	v_pk_fma_f32 v[0:1], v[128:129], v[140:141], v[0:1] op_sel_hi:[1,0,1]
	s_cmp_lt_u32 s40, 7
	s_cbranch_scc1 .Lsg_done_211
	v_mov_b32_e32 v140, v106
	v_pk_fma_f32 v[12:13], v[134:135], v[140:141], v[12:13] op_sel_hi:[1,0,1]
	v_pk_fma_f32 v[0:1], v[132:133], v[140:141], v[0:1] op_sel_hi:[1,0,1]
	s_cmp_lt_u32 s40, 8
	s_cbranch_scc1 .Lsg_done_211
	v_mov_b32_e32 v140, v107
	v_pk_fma_f32 v[12:13], v[138:139], v[140:141], v[12:13] op_sel_hi:[1,0,1]
	v_pk_fma_f32 v[0:1], v[136:137], v[140:141], v[0:1] op_sel_hi:[1,0,1]
.Lsg_done_211:
	s_lshl_b32 s41, s40, 12
	v_add_u32_e32 v4, s41, v4
	s_lshl_b32 s41, s40, 2
	v_mov_b32_e32 v140, s41
	v_mov_b32_e32 v141, 0
	v_lshl_add_u64 v[2:3], v[2:3], 0, v[140:141]
	v_mov_b32_e32 v16, 0
	s_mov_b64 s[38:39], exec
	s_or_b64 exec, exec, s[38:39]
	v_mov_b64_e32 v[4:5], v[2:3]
	v_mov_b64_e32 v[2:3], v[0:1]
	v_mov_b32_e32 v0, v13
